# attention: first queue ticket taken inside seam 1 behind the leader's arrival atomic (round trip hidden in the barrier wait)
# baseline (speedup 1.0000x reference)
.LBB0_226:
	s_mov_b32 s101, 0
	s_cmp_gt_i32 s89, 2
	s_cselect_b64 s[6:7], -1, 0
	s_and_b64 s[8:9], s[36:37], s[6:7]
	s_andn2_b64 vcc, exec, s[8:9]
	s_cbranch_vccnz .LBB0_280
	s_waitcnt vmcnt(0)
	s_waitcnt vmcnt(0) lgkmcnt(0)
	s_barrier
	s_and_saveexec_b64 s[8:9], s[26:27]
	s_cbranch_execz .LBB0_279
	s_add_i32 s10, 0, 0x22020
	v_mov_b32_e32 v0, s10
	s_waitcnt vmcnt(0) expcnt(0) lgkmcnt(0)
	ds_read_b32 v2, v0
	s_add_i32 s10, 0, 0x22024
	v_mov_b32_e32 v0, s10
	ds_read_b32 v0, v0
	s_waitcnt lgkmcnt(1)
	v_cmp_ne_u32_e32 vcc, 0, v2
	s_cbranch_vccnz .LBB0_243
	s_add_u32 s10, s30, 0x40200
	s_addc_u32 s11, s31, 0
	s_add_u32 s12, s30, 0x40400
	s_addc_u32 s13, s31, 0
	s_add_u32 s14, s30, 0x40500
	s_addc_u32 s15, s31, 0
	s_add_u32 s16, s30, 0x40600
	s_addc_u32 s17, s31, 0
	s_add_u32 s18, s30, 0x40700
	s_addc_u32 s19, s31, 0
	s_add_u32 s20, s30, 0x40800
	s_addc_u32 s21, s31, 0
	s_add_u32 s22, s30, 0x40900
	s_addc_u32 s23, s31, 0
	s_add_u32 s24, s30, 0x40a00
	s_addc_u32 s25, s31, 0
	s_add_u32 s36, s30, 0x40b00
	s_addc_u32 s37, s31, 0
	s_add_u32 s38, s30, 0x40c00
	s_addc_u32 s39, s31, 0
	s_add_u32 s40, s30, 0x40d00
	s_addc_u32 s41, s31, 0
	s_add_u32 s42, s30, 0x40e00
	s_addc_u32 s43, s31, 0
	s_add_u32 s44, s30, 0x40f00
	s_addc_u32 s45, s31, 0
	s_add_u32 s46, s30, 0x41000
	s_addc_u32 s47, s31, 0
	s_add_u32 s48, s30, 0x41100
	s_addc_u32 s49, s31, 0
	s_add_u32 s50, s30, 0x41200
	s_addc_u32 s51, s31, 0
	s_mul_i32 s61, s29, s90
	s_add_u32 s52, s30, 0x41300
	s_mul_i32 s61, s61, s28
	s_addc_u32 s53, s31, 0
	s_mov_b32 s62, 1
	v_mov_b32_e32 v16, 0
	s_branch .LBB0_231

.LBB0_243:
	s_mov_b64 s[12:13], exec
	s_lshl_b32 s10, s33, 8
	v_mbcnt_lo_u32_b32 v1, s12, 0
	s_add_u32 s10, s34, s10
	v_mbcnt_hi_u32_b32 v1, s13, v1
	s_addc_u32 s11, s35, 0
	v_cmp_eq_u32_e32 vcc, 0, v1
	s_and_saveexec_b64 s[14:15], vcc
	s_cbranch_execz .LBB0_245
	s_bcnt1_i32_b64 s12, s[12:13]
	v_mov_b32_e32 v3, 0x1000
	v_mov_b32_e32 v4, s12
	global_atomic_add v3, v3, v4, s[10:11] offset:1024 sc0
	v_mov_b32_e32 v22, 1
	s_and_b32 s98, s60, 7
	s_lshl_b32 s98, s98, 8
	s_add_i32 s98, s98, 0x4000
	v_mov_b32_e32 v21, s98
	global_atomic_add v20, v21, v22, s[34:35] sc0
	s_mov_b32 s101, 1

.LBB0_280:
	s_cmp_lt_i32 s3, 3
	s_cselect_b64 s[8:9], -1, 0
	s_and_b64 s[20:21], s[8:9], s[6:7]
	s_andn2_b64 vcc, exec, s[20:21]
	s_cbranch_vccnz .LBB0_517
	s_mov_b64 s[6:7], s[0:1]
	s_mov_b64 s[8:9], s[0:1]
	s_load_dwordx2 s[6:7], s[6:7], 0xa8
	s_mov_b64 s[10:11], s[0:1]
	s_load_dwordx2 s[8:9], s[8:9], 0xa8
	s_load_dwordx2 s[12:13], s[10:11], 0xa8
	s_mov_b64 s[10:11], s[0:1]
	s_load_dwordx2 s[14:15], s[10:11], 0xa8
	s_mov_b64 s[10:11], s[0:1]
	s_load_dwordx2 s[16:17], s[10:11], 0xa8
	s_mov_b64 s[10:11], s[0:1]
	s_load_dwordx2 s[18:19], s[10:11], 0x28
	s_mov_b64 s[10:11], s[0:1]
	s_load_dwordx2 s[22:23], s[10:11], 0x30
	s_mov_b64 s[10:11], s[0:1]
	s_waitcnt vmcnt(0)
	v_lshlrev_b32_e32 v0, 2, v210
	s_waitcnt lgkmcnt(0)
	global_load_dword v1, v0, s[18:19]
	global_load_dword v2, v0, s[22:23]
	v_mbcnt_lo_u32_b32 v0, -1, 0
	v_mbcnt_hi_u32_b32 v0, -1, v0
	v_and_b32_e32 v3, 64, v0
	v_xor_b32_e32 v4, 1, v0
	v_add_u32_e32 v3, 64, v3
	v_cmp_lt_i32_e32 vcc, v4, v3
	v_xor_b32_e32 v5, 2, v0
	v_xor_b32_e32 v6, 4, v0
	v_cndmask_b32_e32 v4, v0, v4, vcc
	v_lshlrev_b32_e32 v4, 2, v4
	v_cmp_lt_i32_e32 vcc, v5, v3
	v_xor_b32_e32 v7, 8, v0
	v_xor_b32_e32 v8, 16, v0
	v_cndmask_b32_e32 v5, v0, v5, vcc
	v_lshlrev_b32_e32 v5, 2, v5
	v_cmp_lt_i32_e32 vcc, v6, v3
	v_xor_b32_e32 v9, 32, v0
	s_load_dwordx2 s[10:11], s[10:11], 0xa8
	v_cndmask_b32_e32 v6, v0, v6, vcc
	v_lshlrev_b32_e32 v6, 2, v6
	v_cmp_lt_i32_e32 vcc, v7, v3
	s_waitcnt lgkmcnt(0)
	s_add_u32 s38, s10, 0x44000
	v_cndmask_b32_e32 v7, v0, v7, vcc
	v_lshlrev_b32_e32 v7, 2, v7
	v_cmp_lt_i32_e32 vcc, v8, v3
	s_addc_u32 s39, s11, 0
	s_waitcnt vmcnt(1)
	v_and_b32_e32 v10, 0x7fffffff, v1
	ds_bpermute_b32 v10, v4, v10
	s_waitcnt vmcnt(0)
	v_and_b32_e32 v11, 0x7fffffff, v2
	ds_bpermute_b32 v4, v4, v11
	v_max_f32_e64 v1, |v1|, |v1|
	v_max_f32_e64 v2, |v2|, |v2|
	s_waitcnt lgkmcnt(1)
	v_max_f32_e32 v10, v10, v10
	v_max_f32_e32 v1, v1, v10
	s_waitcnt lgkmcnt(0)
	v_max_f32_e32 v4, v4, v4
	v_max_f32_e32 v2, v2, v4
	ds_bpermute_b32 v4, v5, v1
	ds_bpermute_b32 v5, v5, v2
	s_waitcnt lgkmcnt(1)
	v_max_f32_e32 v4, v4, v4
	v_max_f32_e32 v1, v1, v4
	s_waitcnt lgkmcnt(0)
	v_max_f32_e32 v4, v5, v5
	v_max_f32_e32 v2, v2, v4
	ds_bpermute_b32 v4, v6, v1
	ds_bpermute_b32 v5, v6, v2
	v_cndmask_b32_e32 v6, v0, v8, vcc
	v_cmp_lt_i32_e32 vcc, v9, v3
	v_lshlrev_b32_e32 v3, 2, v6
	s_waitcnt lgkmcnt(1)
	v_max_f32_e32 v4, v4, v4
	v_max_f32_e32 v1, v1, v4
	s_waitcnt lgkmcnt(0)
	v_max_f32_e32 v4, v5, v5
	v_max_f32_e32 v2, v2, v4
	ds_bpermute_b32 v4, v7, v1
	ds_bpermute_b32 v5, v7, v2
	v_cndmask_b32_e32 v0, v0, v9, vcc
	s_waitcnt lgkmcnt(1)
	v_max_f32_e32 v4, v4, v4
	v_max_f32_e32 v1, v1, v4
	s_waitcnt lgkmcnt(0)
	v_max_f32_e32 v4, v5, v5
	ds_bpermute_b32 v5, v3, v1
	v_max_f32_e32 v2, v2, v4
	ds_bpermute_b32 v3, v3, v2
	v_lshlrev_b32_e32 v4, 2, v0
	s_waitcnt lgkmcnt(1)
	v_max_f32_e32 v0, v5, v5
	v_max_f32_e32 v1, v1, v0
	s_waitcnt lgkmcnt(0)
	v_max_f32_e32 v0, v3, v3
	v_max_f32_e32 v0, v2, v0
	ds_bpermute_b32 v3, v4, v1
	ds_bpermute_b32 v2, v4, v0
	s_and_saveexec_b64 s[10:11], s[26:27]
	s_cbranch_execz .LBB0_315
	s_mov_b64 s[22:23], exec
	v_mbcnt_lo_u32_b32 v4, s22, 0
	v_mbcnt_hi_u32_b32 v4, s23, v4
	s_and_b32 s44, s60, 7
	v_cmp_eq_u32_e32 vcc, 0, v4
	s_and_saveexec_b64 s[18:19], vcc
	s_cbranch_execz .LBB0_284
	s_lshl_b32 s24, s44, 8
	s_bcnt1_i32_b64 s22, s[22:23]
	v_mov_b32_e32 v5, s24
	v_mov_b32_e32 v6, s22
	s_cmp_eq_u32 s101, 1
	s_cbranch_scc1 .Lattn_tk0_have
	global_atomic_add v5, v5, v6, s[38:39] sc0
	s_branch .Lattn_tk0_done
.Lattn_tk0_have:
	v_mov_b32_e32 v5, v20
.Lattn_tk0_done:
.LBB0_284:
	s_or_b64 exec, exec, s[18:19]
	s_waitcnt vmcnt(0)
	v_readfirstlane_b32 s18, v5
	s_mov_b64 s[22:23], -1
	v_mov_b32_e32 v5, s44
	v_add_u32_e32 v4, s18, v4
	s_movk_i32 s18, 0x7f
	v_cmp_lt_u32_e32 vcc, s18, v4
	s_and_saveexec_b64 s[18:19], vcc
	s_cbranch_execz .LBB0_312
	s_mov_b64 s[22:23], exec
	v_mbcnt_lo_u32_b32 v4, s22, 0
	s_add_i32 s24, s60, 1
	v_mbcnt_hi_u32_b32 v4, s23, v4
	s_and_b32 s36, s24, 7
	v_cmp_eq_u32_e32 vcc, 0, v4
	s_and_saveexec_b64 s[24:25], vcc
	s_cbranch_execz .LBB0_287
	s_lshl_b32 s37, s36, 8
	s_bcnt1_i32_b64 s22, s[22:23]
	v_mov_b32_e32 v5, s37
	v_mov_b32_e32 v6, s22
	global_atomic_add v5, v5, v6, s[38:39] sc0
